# remove redundant canonicalizing max ops after cross-lane reductions in compressed-branch and masked attention paths
# speedup vs baseline: 1.0053x; 1.0028x over previous
; #define LAS __attribute__((address_space(3)))
; template <int MODE, bool FAST, bool DEFER>
; __device__ __forceinline__ void attn_tile(AttnState& st, const LAS bf16_t* Ks, const LAS bf16_t* Vt, int jb, int tq, bool mybit, int fr, int fq, float (&imp)[16], float& prev_t3, bf16x8 (&pfo)[2][2]) {
;     ...
;     f32x4 s[2][4];
;     f32x4 zinit[2];
; #pragma unroll
;     for (int ct = 0; ct < 2; ++ct) { const float nb_ = !FAST ? 0.f : ((MODE == M_SLC && !mybit) ? -1e30f : (st.m[ct] < -1e29f ? 0.f : -st.m[ct])); zinit[ct] = (f32x4){nb_, nb_, nb_, nb_}; }
; #pragma unroll
;     for (int sb = 0; sb < 4; ++sb) {
;         const bf16x8 k0 = *(const LAS bf16x8*)(Ks + (sb * 16 + fr) * KSTR + fq * 8);
;         const bf16x8 k1 = *(const LAS bf16x8*)(Ks + (sb * 16 + fr) * KSTR + 32 + fq * 8);
; #pragma unroll
;         for (int ct = 0; ct < 2; ++ct) {
;             f32x4 z = zinit[ct];
;             z = __builtin_amdgcn_mfma_f32_16x16x32_bf16(k0, st.qf[ct][0], z, 0, 0, 0);
;             z = __builtin_amdgcn_mfma_f32_16x16x32_bf16(k1, st.qf[ct][1], z, 0, 0, 0);
;             s[ct][sb] = ISCMP ? z * ATT_QS : z;
;         }
;     }
;     unsigned vbits = 0;
;     if (!FAST) {
; #pragma unroll
;         for (int sb = 0; sb < 4; ++sb)
; #pragma unroll
;             for (int j = 0; j < 4; ++j) {
;                 const int kidx = jb * 64 + sb * 16 + fq * 4 + j;
;                 bool v;
;                 if (ISCMP) v = (16 * kidx + 31 <= tq);
;                 else if (MODE == M_SLC) v = mybit && (kidx <= tq);
;                 else v = (kidx <= tq) && (tq - kidx < 512);
;                 vbits |= (v ? 1u : 0u) << (sb * 4 + j);
;             }
;     }
;     ...
;     float tmaxv[2]; bool need[2];
; #pragma unroll
;     for (int ct = 0; ct < 2; ++ct) {
;         float tmax = -1e30f;
; #pragma unroll
;         for (int sb = 0; sb < 4; ++sb)
; #pragma unroll
;             for (int j = 0; j < 4; ++j) {
;                 if (!FAST) s[ct][sb][j] = ((vbits >> (sb * 4 + j)) & 1u) ? s[ct][sb][j] : -1e30f;
;                 tmax = fmaxf(tmax, s[ct][sb][j]);
;             }
;         if (FAST && MODE == M_SLC) tmax = mybit ? tmax : -1e30f;
;         tmax = fmaxf(tmax, __shfl_xor(tmax, 16)); tmax = fmaxf(tmax, __shfl_xor(tmax, 32));
;         tmaxv[ct] = tmax; need[ct] = tmax > st.m[ct] + ATT_THR;
;     }
;     if (__builtin_amdgcn_ballot_w64(need[0] || need[1]) != 0ull) {
.LBB0_1012:
	v_add3_u32 v45, v24, v164, v183
	s_waitcnt lgkmcnt(0)
	s_barrier
	ds_read_b128 v[24:27], v45
	ds_read_b128 v[28:31], v45 offset:64
	s_waitcnt lgkmcnt(1)
	v_mfma_f32_16x16x32_bf16 v[32:35], v[24:27], v[2:5], 0
	s_mov_b32 s0, 0x3e38aa3b
	v_mfma_f32_16x16x32_bf16 v[24:27], v[24:27], v[10:13], 0
	s_waitcnt lgkmcnt(0)
	v_mfma_f32_16x16x32_bf16 v[34:37], v[28:31], v[6:9], v[32:35]
	v_mfma_f32_16x16x32_bf16 v[26:29], v[28:31], v[14:17], v[24:27]
	s_nop 6
	v_mul_f32_e64 v32, v36, s0
	v_mul_f32_e64 v33, v37, s0
	v_pk_mul_f32 v[24:25], v[28:29], s[0:1] op_sel_hi:[1,0]
	ds_read_b128 v[28:31], v45 offset:2304
	ds_read_b128 v[36:39], v45 offset:2368
	s_waitcnt lgkmcnt(1)
	v_mfma_f32_16x16x32_bf16 v[46:49], v[28:31], v[2:5], 0
	v_mul_f32_e64 v34, v34, s0
	v_mul_f32_e64 v35, v35, s0
	v_pk_mul_f32 v[26:27], v[26:27], s[0:1] op_sel_hi:[1,0]
	v_mfma_f32_16x16x32_bf16 v[28:31], v[28:31], v[10:13], 0
	s_waitcnt lgkmcnt(0)
	v_mfma_f32_16x16x32_bf16 v[46:49], v[36:39], v[6:9], v[46:49]
	v_mfma_f32_16x16x32_bf16 v[36:39], v[36:39], v[14:17], v[28:31]
	s_nop 6
	v_mul_f32_e64 v66, v48, s0
	v_mul_f32_e64 v67, v49, s0
	v_pk_mul_f32 v[58:59], v[46:47], s[0:1] op_sel_hi:[1,0]
	v_pk_mul_f32 v[28:29], v[38:39], s[0:1] op_sel_hi:[1,0]
	v_pk_mul_f32 v[30:31], v[36:37], s[0:1] op_sel_hi:[1,0]
	ds_read_b128 v[36:39], v45 offset:4608
	ds_read_b128 v[46:49], v45 offset:4672
	s_waitcnt lgkmcnt(1)
	v_mfma_f32_16x16x32_bf16 v[50:53], v[36:39], v[2:5], 0
	v_mfma_f32_16x16x32_bf16 v[36:39], v[36:39], v[10:13], 0
	s_waitcnt lgkmcnt(0)
	v_mfma_f32_16x16x32_bf16 v[50:53], v[46:49], v[6:9], v[50:53]
	v_mfma_f32_16x16x32_bf16 v[46:49], v[46:49], v[14:17], v[36:39]
	s_nop 6
	v_mul_f32_e64 v68, v52, s0
	v_mul_f32_e64 v69, v53, s0
	v_pk_mul_f32 v[70:71], v[50:51], s[0:1] op_sel_hi:[1,0]
	v_pk_mul_f32 v[36:37], v[48:49], s[0:1] op_sel_hi:[1,0]
	v_pk_mul_f32 v[38:39], v[46:47], s[0:1] op_sel_hi:[1,0]
	ds_read_b128 v[46:49], v45 offset:6912
	ds_read_b128 v[50:53], v45 offset:6976
	s_waitcnt lgkmcnt(1)
	v_mfma_f32_16x16x32_bf16 v[54:57], v[46:49], v[2:5], 0
	v_lshl_or_b32 v45, s4, 10, v165
	v_or_b32_e32 v60, 0x310, v45
	v_cmp_gt_i32_e64 s[4:5], v60, v92
	v_mfma_f32_16x16x32_bf16 v[46:49], v[46:49], v[10:13], 0
	v_cmp_gt_i32_e64 s[62:63], v45, v92
	v_cndmask_b32_e64 v60, v224, 0, s[4:5]
	s_waitcnt lgkmcnt(0)
	v_mfma_f32_16x16x32_bf16 v[54:57], v[50:53], v[6:9], v[54:57]
	v_cndmask_b32_e64 v64, v34, v227, s[62:63]
	v_mfma_f32_16x16x32_bf16 v[46:49], v[50:53], v[14:17], v[46:49]
	v_or_b32_e32 v52, 0x130, v45
	s_nop 4
	v_pk_mul_f32 v[74:75], v[54:55], s[0:1] op_sel_hi:[1,0]
	v_or_b32_e32 v54, 0x210, v45
	v_or_b32_e32 v55, 0x220, v45
	v_or_b32_e32 v53, 0x200, v45
	v_cmp_gt_i32_e64 s[48:49], v54, v92
	v_cmp_gt_i32_e64 s[42:43], v55, v92
	v_pk_mul_f32 v[78:79], v[46:47], s[0:1] op_sel_hi:[1,0]
	v_or_b32_e32 v46, 16, v45
	v_or_b32_e32 v47, 32, v45
	v_cmp_gt_i32_e64 s[52:53], v52, v92
	v_cmp_gt_i32_e64 s[46:47], v53, v92
	v_cndmask_b32_e64 v54, v220, 0, s[48:49]
	v_cndmask_b32_e64 v55, v221, 0, s[42:43]
	v_pk_mul_f32 v[76:77], v[48:49], s[0:1] op_sel_hi:[1,0]
	v_cmp_gt_i32_e64 s[64:65], v46, v92
	v_cmp_gt_i32_e64 s[58:59], v47, v92
	v_or_b32_e32 v48, 48, v45
	v_or_b32_e32 v49, 0x100, v45
	v_cndmask_b32_e64 v52, v218, 0, s[52:53]
	v_cndmask_b32_e64 v53, v219, 0, s[46:47]
	v_or3_b32 v54, v54, v55, v60
	v_cndmask_b32_e64 v46, 2, 0, s[64:65]
	v_cndmask_b32_e64 v47, 4, 0, s[58:59]
	v_cmp_gt_i32_e64 s[60:61], v48, v92
	v_cmp_gt_i32_e64 s[54:55], v49, v92
	v_or_b32_e32 v50, 0x110, v45
	v_or_b32_e32 v51, 0x120, v45
	v_or3_b32 v52, v52, v53, v54
	v_pk_mul_f32 v[72:73], v[56:57], s[0:1] op_sel_hi:[1,0]
	v_cndmask_b32_e64 v48, 8, 0, s[60:61]
	v_cndmask_b32_e64 v49, 16, 0, s[54:55]
	v_cmp_gt_i32_e64 s[56:57], v50, v92
	v_cmp_gt_i32_e64 s[50:51], v51, v92
	v_or_b32_e32 v56, 0x230, v45
	v_or_b32_e32 v57, 0x300, v45
	v_or3_b32 v46, v46, v47, v52
	v_cndmask_b32_e64 v50, 32, 0, s[56:57]
	v_cndmask_b32_e64 v51, 64, 0, s[50:51]
	v_cmp_gt_i32_e64 s[44:45], v56, v92
	v_cmp_gt_i32_e64 s[8:9], v57, v92
	v_or3_b32 v46, v48, v49, v46
	v_cndmask_b32_e64 v63, v35, v227, s[64:65]
	v_cndmask_b32_e64 v56, v222, 0, s[44:45]
	v_cndmask_b32_e64 v57, v223, 0, s[8:9]
	v_or3_b32 v46, v50, v51, v46
	v_max3_f32 v34, v64, s36, v63
	v_cndmask_b32_e64 v62, v32, v227, s[58:59]
	v_cndmask_b32_e64 v61, v33, v227, s[60:61]
	v_or3_b32 v47, v57, v56, v46
	v_or_b32_e32 v46, 0x320, v45
	v_max3_f32 v32, v34, v62, v61
	v_cndmask_b32_e64 v60, v58, v227, s[54:55]
	v_cndmask_b32_e64 v59, v59, v227, s[56:57]
	v_cmp_gt_i32_e32 vcc, v46, v92
	v_or_b32_e32 v45, 0x330, v45
	v_max3_f32 v32, v32, v60, v59
	v_cndmask_b32_e64 v58, v66, v227, s[50:51]
	v_cndmask_b32_e64 v56, v67, v227, s[52:53]
	v_cndmask_b32_e64 v46, v225, 0, vcc
	v_cmp_gt_i32_e32 vcc, v45, v92
	v_max3_f32 v32, v32, v58, v56
	v_cndmask_b32_e64 v54, v70, v227, s[46:47]
	v_cndmask_b32_e64 v52, v71, v227, s[48:49]
	v_cndmask_b32_e64 v45, v226, 0, vcc
	v_max3_f32 v32, v32, v54, v52
	v_cndmask_b32_e64 v50, v68, v227, s[42:43]
	v_cndmask_b32_e64 v48, v69, v227, s[44:45]
	v_or_b32_e32 v45, v46, v45
	v_max3_f32 v32, v32, v50, v48
	v_cndmask_b32_e64 v46, v74, v227, s[8:9]
	v_cndmask_b32_e64 v35, v75, v227, s[4:5]
	v_max3_f32 v34, v32, v46, v35
	v_bitop3_b32 v32, v45, s34, v47 bitop3:0xc8
	v_cmp_eq_u32_e64 s[66:67], 0, v32
	v_bitop3_b32 v32, v45, s35, v47 bitop3:0xc8
	v_cmp_eq_u32_e64 s[68:69], 0, v32
	v_cndmask_b32_e64 v33, v72, v227, s[66:67]
	v_cndmask_b32_e64 v57, v26, v227, s[62:63]
	v_cndmask_b32_e64 v32, v73, v227, s[68:69]
	v_max3_f32 v34, v34, v33, v32
	ds_bpermute_b32 v45, v185, v34
	v_cndmask_b32_e64 v55, v27, v227, s[64:65]
	v_max3_f32 v26, v57, s36, v55
	v_cndmask_b32_e64 v53, v24, v227, s[58:59]
	v_cndmask_b32_e64 v51, v25, v227, s[60:61]
	s_waitcnt lgkmcnt(0)
	v_max_f32_e32 v34, v34, v45
	ds_bpermute_b32 v45, v153, v34
	v_max3_f32 v24, v26, v53, v51
	v_cndmask_b32_e64 v49, v30, v227, s[54:55]
	v_cndmask_b32_e64 v47, v31, v227, s[56:57]
	v_max3_f32 v24, v24, v49, v47
	s_waitcnt lgkmcnt(0)
	v_max_f32_e32 v65, v34, v45
	v_add_f32_e32 v34, 0x40c00000, v154
	v_cmp_gt_f32_e64 s[0:1], v65, v34
	v_cndmask_b32_e64 v45, v28, v227, s[50:51]
	v_cndmask_b32_e64 v34, v29, v227, s[52:53]
	v_max3_f32 v24, v24, v45, v34
	v_cndmask_b32_e64 v31, v38, v227, s[46:47]
	v_cndmask_b32_e64 v30, v39, v227, s[48:49]
	v_max3_f32 v24, v24, v31, v30
	v_cndmask_b32_e64 v29, v36, v227, s[42:43]
	v_cndmask_b32_e64 v28, v37, v227, s[44:45]
	v_max3_f32 v24, v24, v29, v28
	v_cndmask_b32_e64 v27, v78, v227, s[8:9]
	v_cndmask_b32_e64 v26, v79, v227, s[4:5]
	v_max3_f32 v36, v24, v27, v26
	v_cndmask_b32_e64 v25, v76, v227, s[66:67]
	v_cndmask_b32_e64 v24, v77, v227, s[68:69]
	v_max3_f32 v36, v36, v25, v24
	ds_bpermute_b32 v37, v185, v36
	s_waitcnt lgkmcnt(0)
	v_max_f32_e32 v36, v36, v37
	ds_bpermute_b32 v37, v153, v36
	s_waitcnt lgkmcnt(0)
	v_max_f32_e32 v36, v36, v37
	v_add_f32_e32 v37, 0x40c00000, v155
	v_cmp_gt_f32_e64 s[6:7], v36, v37
	s_or_b64 vcc, s[0:1], s[6:7]
	s_cbranch_vccz .LBB0_1014
; template <int MODE, bool FAST, bool DEFER>
; __device__ __forceinline__ void attn_tile(AttnState& st, const LAS bf16_t* Ks, const LAS bf16_t* Vt, int jb, int tq, bool mybit, int fr, int fq, float (&imp)[16], float& prev_t3, bf16x8 (&pfo)[2][2]) {
;     ...
;     if (__builtin_amdgcn_ballot_w64(need[0] || need[1]) != 0ull) {
; #pragma unroll
;         for (int ct = 0; ct < 2; ++ct) {
;             const float alpha = need[ct] ? __builtin_amdgcn_exp2f(st.m[ct] - tmaxv[ct]) : 1.f;
;             st.m[ct] = need[ct] ? tmaxv[ct] : st.m[ct];
;             st.l[ct] *= alpha;
;             if (MODE != M_CMP1) {
; #pragma unroll
;                 for (int dt = 0; dt < 4; ++dt) st.o[ct][dt] = st.o[ct][dt] * alpha;
;             }
;         }
;     }
	v_sub_f32_e32 v37, v154, v65
	v_sub_f32_e32 v38, v155, v36
	v_exp_f32_e32 v37, v37
	v_exp_f32_e32 v38, v38
	v_cndmask_b32_e64 v155, v155, v36, s[6:7]
	v_cndmask_b32_e64 v154, v154, v65, s[0:1]
	v_cndmask_b32_e64 v37, 1.0, v37, s[0:1]
	v_cndmask_b32_e64 v36, 1.0, v38, s[6:7]
	v_mul_f32_e32 v41, v41, v37
	v_mul_f32_e32 v43, v43, v36

; template <int MODE, bool FAST, bool DEFER>
; __device__ __forceinline__ void attn_tile(AttnState& st, const LAS bf16_t* Ks, const LAS bf16_t* Vt, int jb, int tq, bool mybit, int fr, int fq, float (&imp)[16], float& prev_t3, bf16x8 (&pfo)[2][2]) {
;     ...
;     f32x4 s[2][4];
;     f32x4 zinit[2];
; #pragma unroll
;     for (int ct = 0; ct < 2; ++ct) { const float nb_ = !FAST ? 0.f : ((MODE == M_SLC && !mybit) ? -1e30f : (st.m[ct] < -1e29f ? 0.f : -st.m[ct])); zinit[ct] = (f32x4){nb_, nb_, nb_, nb_}; }
; #pragma unroll
;     for (int sb = 0; sb < 4; ++sb) {
;         const bf16x8 k0 = *(const LAS bf16x8*)(Ks + (sb * 16 + fr) * KSTR + fq * 8);
;         const bf16x8 k1 = *(const LAS bf16x8*)(Ks + (sb * 16 + fr) * KSTR + 32 + fq * 8);
; #pragma unroll
;         for (int ct = 0; ct < 2; ++ct) {
;             f32x4 z = zinit[ct];
;             z = __builtin_amdgcn_mfma_f32_16x16x32_bf16(k0, st.qf[ct][0], z, 0, 0, 0);
;             z = __builtin_amdgcn_mfma_f32_16x16x32_bf16(k1, st.qf[ct][1], z, 0, 0, 0);
;             s[ct][sb] = ISCMP ? z * ATT_QS : z;
;         }
;     }
;     unsigned vbits = 0;
;     if (!FAST) {
; #pragma unroll
;         for (int sb = 0; sb < 4; ++sb)
; #pragma unroll
;             for (int j = 0; j < 4; ++j) {
;                 const int kidx = jb * 64 + sb * 16 + fq * 4 + j;
;                 bool v;
;                 if (ISCMP) v = (16 * kidx + 31 <= tq);
;                 else if (MODE == M_SLC) v = mybit && (kidx <= tq);
;                 else v = (kidx <= tq) && (tq - kidx < 512);
;                 vbits |= (v ? 1u : 0u) << (sb * 4 + j);
;             }
;     }
;     ...
;     float tmaxv[2]; bool need[2];
; #pragma unroll
;     for (int ct = 0; ct < 2; ++ct) {
;         float tmax = -1e30f;
; #pragma unroll
;         for (int sb = 0; sb < 4; ++sb)
; #pragma unroll
;             for (int j = 0; j < 4; ++j) {
;                 if (!FAST) s[ct][sb][j] = ((vbits >> (sb * 4 + j)) & 1u) ? s[ct][sb][j] : -1e30f;
;                 tmax = fmaxf(tmax, s[ct][sb][j]);
;             }
;         if (FAST && MODE == M_SLC) tmax = mybit ? tmax : -1e30f;
;         tmax = fmaxf(tmax, __shfl_xor(tmax, 16)); tmax = fmaxf(tmax, __shfl_xor(tmax, 32));
;         tmaxv[ct] = tmax; need[ct] = tmax > st.m[ct] + ATT_THR;
;     }
;     if (__builtin_amdgcn_ballot_w64(need[0] || need[1]) != 0ull) {
; #pragma unroll
;         for (int ct = 0; ct < 2; ++ct) {
.LBB0_1152:
	s_and_b64 vcc, exec, s[0:1]
	s_cbranch_vccz .LBB0_1156
	v_add3_u32 v88, v193, v164, v183
	ds_read_b128 v[60:63], v88
	ds_read_b128 v[64:67], v88 offset:64
	v_readlane_b32 s0, v254, 19
	v_readlane_b32 s1, v254, 20
	s_and_b64 s[72:73], s[70:71], s[0:1]
	s_waitcnt lgkmcnt(1)
	v_mfma_f32_16x16x32_bf16 v[68:71], v[60:63], v[4:7], 0
	v_readlane_b32 s0, v254, 21
	s_and_b64 s[84:85], s[70:71], s[56:57]
	s_and_b64 s[78:79], s[70:71], s[58:59]
	v_mfma_f32_16x16x32_bf16 v[60:63], v[60:63], v[12:15], 0
	s_and_b64 s[76:77], s[70:71], s[64:65]
	v_readlane_b32 s1, v254, 22
	s_and_b64 s[88:89], s[70:71], s[52:53]
	s_waitcnt lgkmcnt(0)
	v_mfma_f32_16x16x32_bf16 v[68:71], v[64:67], v[8:11], v[68:71]
	s_and_b64 s[82:83], s[70:71], s[54:55]
	s_and_b64 s[96:97], s[70:71], s[0:1]
	s_and_b64 s[94:95], s[70:71], s[42:43]
	v_mfma_f32_16x16x32_bf16 v[60:63], v[64:67], v[16:19], v[60:63]
	ds_read_b128 v[64:67], v88 offset:2304
	ds_read_b128 v[72:75], v88 offset:2368
	s_and_b64 s[8:9], s[70:71], s[44:45]
	s_and_b64 s[90:91], s[70:71], s[46:47]
	s_waitcnt lgkmcnt(1)
	v_mfma_f32_16x16x32_bf16 v[76:79], v[64:67], v[4:7], 0
	s_and_b64 s[92:93], s[70:71], s[48:49]
	s_and_b64 s[86:87], s[70:71], s[50:51]
	s_and_b64 s[80:81], s[70:71], s[60:61]
	v_mfma_f32_16x16x32_bf16 v[64:67], v[64:67], v[12:15], 0
	s_and_b64 s[74:75], s[70:71], s[62:63]
	s_and_b64 vcc, s[70:71], s[66:67]
	v_cndmask_b32_e64 v91, v227, v68, s[72:73]
	s_waitcnt lgkmcnt(0)
	v_mfma_f32_16x16x32_bf16 v[76:79], v[72:75], v[8:11], v[76:79]
	v_cndmask_b32_e64 v90, v227, v69, s[96:97]
	v_max3_f32 v68, v91, s36, v90
	v_cndmask_b32_e64 v89, v227, v70, s[94:95]
	v_mfma_f32_16x16x32_bf16 v[64:67], v[72:75], v[16:19], v[64:67]
	ds_read_b128 v[72:75], v88 offset:4608
	ds_read_b128 v[80:83], v88 offset:4672
	s_waitcnt lgkmcnt(1)
	v_mfma_f32_16x16x32_bf16 v[84:87], v[72:75], v[4:7], 0
	v_mfma_f32_16x16x32_bf16 v[72:75], v[72:75], v[12:15], 0
	s_waitcnt lgkmcnt(0)
	v_mfma_f32_16x16x32_bf16 v[92:95], v[80:83], v[8:11], v[84:87]
	v_mfma_f32_16x16x32_bf16 v[96:99], v[80:83], v[16:19], v[72:75]
	s_nop 4
	ds_read_b128 v[72:75], v88 offset:6912
	ds_read_b128 v[80:83], v88 offset:6976
	v_cndmask_b32_e64 v88, 0, v224, s[76:77]
	s_waitcnt lgkmcnt(1)
	v_mfma_f32_16x16x32_bf16 v[84:87], v[72:75], v[4:7], 0
	v_mfma_f32_16x16x32_bf16 v[72:75], v[72:75], v[12:15], 0
	s_waitcnt lgkmcnt(0)
	v_mfma_f32_16x16x32_bf16 v[100:103], v[80:83], v[8:11], v[84:87]
	s_nop 4
	v_cndmask_b32_e64 v84, 0, v220, s[84:85]
	v_cndmask_b32_e64 v85, 0, v221, s[78:79]
	v_mfma_f32_16x16x32_bf16 v[104:107], v[80:83], v[16:19], v[72:75]
	v_cndmask_b32_e64 v82, 0, v218, s[88:89]
	v_cndmask_b32_e64 v83, 0, v219, s[82:83]
	v_or3_b32 v84, v84, v85, v88
	v_cndmask_b32_e64 v72, 0, 2, s[96:97]
	v_cndmask_b32_e64 v73, 0, 4, s[94:95]
	v_or3_b32 v82, v82, v83, v84
	v_cndmask_b32_e64 v74, 0, 8, s[8:9]
	v_cndmask_b32_e64 v75, 0, 16, s[90:91]
	v_or3_b32 v72, v72, v73, v82
	v_cndmask_b32_e64 v80, 0, 32, s[92:93]
	v_cndmask_b32_e64 v81, 0, 64, s[86:87]
	v_or3_b32 v72, v74, v75, v72
	v_cndmask_b32_e64 v86, 0, v222, s[80:81]
	v_cndmask_b32_e64 v87, 0, v223, s[74:75]
	v_or3_b32 v72, v80, v81, v72
	v_cndmask_b32_e32 v73, 0, v225, vcc
	s_and_b64 vcc, s[70:71], s[68:69]
	v_cndmask_b32_e64 v88, v227, v71, s[8:9]
	v_or3_b32 v72, v87, v86, v72
	v_cndmask_b32_e32 v74, 0, v226, vcc
	v_max3_f32 v68, v68, v89, v88
	v_cndmask_b32_e64 v87, v227, v76, s[90:91]
	v_cndmask_b32_e64 v86, v227, v77, s[92:93]
	v_or_b32_e32 v73, v73, v74
	v_max3_f32 v68, v68, v87, v86
	v_cndmask_b32_e64 v85, v227, v78, s[86:87]
	v_cndmask_b32_e64 v84, v227, v79, s[88:89]
	v_max3_f32 v68, v68, v85, v84
	v_cndmask_b32_e64 v83, v227, v92, s[82:83]
	v_cndmask_b32_e64 v82, v227, v93, s[84:85]
	v_bitop3_b32 v69, v73, s34, v72 bitop3:0xc8
	v_max3_f32 v68, v68, v83, v82
	v_cndmask_b32_e64 v79, v227, v94, s[78:79]
	v_cndmask_b32_e64 v78, v227, v95, s[80:81]
	v_cmp_eq_u32_e64 s[70:71], 0, v69
	v_bitop3_b32 v69, v73, s35, v72 bitop3:0xc8
	v_max3_f32 v68, v68, v79, v78
	v_cndmask_b32_e64 v75, v227, v100, s[74:75]
	v_cndmask_b32_e64 v74, v227, v101, s[76:77]
	v_cmp_eq_u32_e64 s[4:5], 0, v69
	v_max3_f32 v68, v68, v75, v74
	v_cndmask_b32_e64 v71, v102, v227, s[70:71]
	v_cndmask_b32_e64 v70, v103, v227, s[4:5]
	v_max3_f32 v68, v68, v71, v70
	ds_bpermute_b32 v69, v185, v68
	v_cndmask_b32_e64 v81, v227, v60, s[72:73]
	v_cndmask_b32_e64 v80, v227, v61, s[96:97]
	v_max3_f32 v60, v81, s36, v80
	v_cndmask_b32_e64 v77, v227, v62, s[94:95]
	s_waitcnt lgkmcnt(0)
	v_max_f32_e32 v68, v68, v69
	ds_bpermute_b32 v69, v153, v68
	v_cndmask_b32_e64 v76, v227, v63, s[8:9]
	v_max3_f32 v60, v60, v77, v76
	v_cndmask_b32_e64 v73, v227, v64, s[90:91]
	v_cndmask_b32_e64 v72, v227, v65, s[92:93]
	s_waitcnt lgkmcnt(0)
	v_max_f32_e32 v92, v68, v69
	v_add_f32_e32 v68, 0x40c00000, v190
	v_cmp_gt_f32_e64 s[0:1], v92, v68
	v_max3_f32 v60, v60, v73, v72
	v_cndmask_b32_e64 v69, v227, v66, s[86:87]
	v_cndmask_b32_e64 v68, v227, v67, s[88:89]
	v_max3_f32 v60, v60, v69, v68
	v_cndmask_b32_e64 v67, v227, v96, s[82:83]
	v_cndmask_b32_e64 v66, v227, v97, s[84:85]
	v_max3_f32 v60, v60, v67, v66
	v_cndmask_b32_e64 v65, v227, v98, s[78:79]
	v_cndmask_b32_e64 v64, v227, v99, s[80:81]
	v_max3_f32 v60, v60, v65, v64
	v_cndmask_b32_e64 v63, v227, v104, s[74:75]
	v_cndmask_b32_e64 v62, v227, v105, s[76:77]
	v_max3_f32 v93, v60, v63, v62
	v_cndmask_b32_e64 v61, v106, v227, s[70:71]
	v_cndmask_b32_e64 v60, v107, v227, s[4:5]
	v_max3_f32 v93, v93, v61, v60
	ds_bpermute_b32 v94, v185, v93
	s_waitcnt lgkmcnt(0)
	v_max_f32_e32 v93, v93, v94
	ds_bpermute_b32 v94, v153, v93
	s_waitcnt lgkmcnt(0)
	v_max_f32_e32 v93, v93, v94
	v_add_f32_e32 v94, 0x40c00000, v191
	v_cmp_gt_f32_e64 s[6:7], v93, v94
	s_or_b64 vcc, s[0:1], s[6:7]
	s_cbranch_vccz .LBB0_1155
	v_sub_f32_e32 v94, v190, v92
	v_exp_f32_e32 v94, v94
	v_cndmask_b32_e64 v190, v190, v92, s[0:1]
	v_cndmask_b32_e64 v92, 1.0, v94, s[0:1]
	v_sub_f32_e32 v94, v191, v93
	v_exp_f32_e32 v94, v94
	v_mul_f32_e32 v159, v159, v92
	v_pk_mul_f32 v[46:47], v[46:47], v[92:93] op_sel_hi:[1,0]
	v_pk_mul_f32 v[44:45], v[44:45], v[92:93] op_sel_hi:[1,0]
	v_pk_mul_f32 v[50:51], v[50:51], v[92:93] op_sel_hi:[1,0]
	v_pk_mul_f32 v[48:49], v[48:49], v[92:93] op_sel_hi:[1,0]
	v_pk_mul_f32 v[54:55], v[54:55], v[92:93] op_sel_hi:[1,0]
	v_pk_mul_f32 v[52:53], v[52:53], v[92:93] op_sel_hi:[1,0]
	v_pk_mul_f32 v[58:59], v[58:59], v[92:93] op_sel_hi:[1,0]
	v_pk_mul_f32 v[56:57], v[56:57], v[92:93] op_sel_hi:[1,0]
	v_cndmask_b32_e64 v92, 1.0, v94, s[6:7]
	v_cndmask_b32_e64 v191, v191, v93, s[6:7]
	v_mul_f32_e32 v158, v158, v92
	v_pk_mul_f32 v[30:31], v[30:31], v[92:93] op_sel_hi:[1,0]
	v_pk_mul_f32 v[28:29], v[28:29], v[92:93] op_sel_hi:[1,0]
	v_pk_mul_f32 v[34:35], v[34:35], v[92:93] op_sel_hi:[1,0]
	v_pk_mul_f32 v[32:33], v[32:33], v[92:93] op_sel_hi:[1,0]
	v_pk_mul_f32 v[26:27], v[26:27], v[92:93] op_sel_hi:[1,0]
	v_pk_mul_f32 v[24:25], v[24:25], v[92:93] op_sel_hi:[1,0]
	v_pk_mul_f32 v[22:23], v[22:23], v[92:93] op_sel_hi:[1,0]
	v_pk_mul_f32 v[20:21], v[20:21], v[92:93] op_sel_hi:[1,0]
